# st1 q up-proj RoPE epilogue: cos/sin rows at +0 and +32 loaded together per rotary block (8 fewer serial round trips per tile)
# baseline (speedup 1.0000x reference)
.LBB0_1230:
	s_and_b64 vcc, exec, s[2:3]
	s_cbranch_vccz .LBB0_1248
	ds_read_b32 v130, v210
	v_or_b32_e32 v128, v163, v139
	v_mul_u32_u24_e32 v131, 0xaaab, v162
	v_ashrrev_i32_e32 v129, 31, v128
	v_lshlrev_b64 v[172:173], 4, v[128:129]
	s_waitcnt lgkmcnt(0)
	v_mul_f32_e32 v130, 0x3e16c740, v130
	v_lshrrev_b32_e32 v163, 22, v131
	s_movk_i32 s0, 0xffa0
	v_mul_f32_e32 v132, v118, v130
	v_pk_mul_f32 v[166:167], v[112:113], v[130:131] op_sel_hi:[1,0]
	v_pk_mul_f32 v[170:171], v[114:115], v[130:131] op_sel_hi:[1,0]
	v_mov_b32_e32 v118, v127
	v_mad_i32_i24 v112, v163, s0, v162
	v_lshlrev_b64 v[114:115], 2, v[172:173]
	v_pk_mul_f32 v[120:121], v[120:121], v[130:131] op_sel_hi:[1,0]
	v_pk_mul_f32 v[122:123], v[122:123], v[130:131] op_sel_hi:[1,0]
	v_pk_mul_f32 v[164:165], v[116:117], v[130:131] op_sel_hi:[1,0]
	v_pk_mul_f32 v[124:125], v[124:125], v[130:131] op_sel_hi:[1,0]
	v_mul_f32_e32 v134, v126, v130
	v_pk_mul_f32 v[126:127], v[118:119], v[130:131] op_sel_hi:[1,0]
	v_cmp_eq_u32_e32 vcc, 64, v112
	v_lshl_add_u64 v[118:119], v[148:149], 0, v[114:115]
	v_lshl_add_u64 v[116:117], v[150:151], 0, v[114:115]
	s_and_saveexec_b64 s[2:3], vcc
	s_cbranch_execz .LBB0_1233
	global_load_dwordx4 v[172:175], v[118:119], off
	global_load_dwordx4 v[176:179], v[116:117], off
	global_load_dwordx4 v[236:239], v[118:119], off offset:32
	global_load_dwordx4 v[240:243], v[116:117], off offset:32
	v_mov_b32_e32 v135, v126
	v_mov_b32_e32 v133, v127
	s_waitcnt vmcnt(0)
	v_pk_mul_f32 v[114:115], v[120:121], v[176:177]
	s_nop 0
	v_pk_fma_f32 v[114:115], v[166:167], v[172:173], v[114:115] neg_lo:[0,0,1] neg_hi:[0,0,1]
	v_pk_mul_f32 v[166:167], v[166:167], v[176:177]
	s_nop 0
	v_pk_fma_f32 v[120:121], v[120:121], v[172:173], v[166:167]
	v_pk_mul_f32 v[166:167], v[122:123], v[178:179]
	s_nop 0
	v_pk_fma_f32 v[180:181], v[170:171], v[174:175], v[166:167] neg_lo:[0,0,1] neg_hi:[0,0,1]
	v_pk_mul_f32 v[166:167], v[170:171], v[178:179]
	s_nop 0
	v_pk_fma_f32 v[122:123], v[122:123], v[174:175], v[166:167]
	v_pk_mul_f32 v[166:167], v[124:125], v[240:241]
	s_nop 0
	v_pk_fma_f32 v[178:179], v[164:165], v[236:237], v[166:167] neg_lo:[0,0,1] neg_hi:[0,0,1]
	v_pk_mul_f32 v[164:165], v[164:165], v[240:241]
	v_mul_f32_e32 v166, v132, v242
	v_pk_fma_f32 v[124:125], v[124:125], v[236:237], v[164:165]
	v_mul_f32_e32 v164, v134, v238
	v_pk_mul_f32 v[134:135], v[134:135], v[242:243]
	v_mov_b32_e32 v176, v239
	v_mov_b32_e32 v177, v243
	v_pk_mul_f32 v[126:127], v[126:127], v[176:177]
	v_pk_fma_f32 v[132:133], v[132:133], v[238:239], v[134:135] neg_lo:[0,0,1] neg_hi:[0,0,1]
	v_mov_b32_e32 v165, v126
	v_mov_b32_e32 v167, v127
	v_pk_add_f32 v[134:135], v[164:165], v[166:167]
	v_mov_b32_e32 v166, v114
	v_mov_b32_e32 v167, v115
	v_mov_b32_e32 v170, v180
	v_mov_b32_e32 v171, v181
	v_mov_b32_e32 v164, v178
	v_mov_b32_e32 v165, v179
	v_mov_b32_e32 v127, v133
	v_mov_b32_e32 v126, v135
	v_mov_b32_e32 v172, v238
	v_mov_b32_e32 v173, v239
	v_mov_b32_e32 v174, v240
	v_mov_b32_e32 v175, v241
.LBB0_1233:
	s_or_b64 exec, exec, s[2:3]
	v_and_b32_e32 v133, -8, v215
	v_add_u32_e32 v114, v133, v163
	v_ashrrev_i32_e32 v115, 31, v114
	v_and_b32_e32 v129, 0x1f9f, v128
	v_lshlrev_b64 v[114:115], 13, v[114:115]
	v_or_b32_e32 v113, v114, v129
	v_mov_b64_e32 v[172:173], s[20:21]
	v_mad_u64_u32 v[172:173], s[0:1], v113, s77, v[172:173]
	v_mad_i32_i24 v173, v115, s77, v173
	v_ashrrev_i32_e32 v113, 31, v112
	v_lshl_add_u64 v[172:173], v[112:113], 1, v[172:173]
	v_lshlrev_b32_e32 v168, 1, v138
	v_lshl_add_u64 v[172:173], v[172:173], 0, v[168:169]
	v_cvt_pk_bf16_f32 v120, v120, v121
	v_cvt_pk_bf16_f32 v121, v122, v123
	global_store_dwordx2 v[172:173], v[120:121], off offset:32
	v_cvt_pk_bf16_f32 v120, v124, v125
	v_cvt_pk_bf16_f32 v121, v134, v126
	global_store_dwordx2 v[172:173], v[120:121], off offset:48
	v_or_b32_e32 v121, 32, v162
	v_mul_u32_u24_e32 v120, 0xaaab, v121
	v_mov_b32_e32 v131, v130
	v_cvt_pk_bf16_f32 v164, v164, v165
	v_cvt_pk_bf16_f32 v165, v132, v127
	v_lshrrev_b32_e32 v132, 22, v120
	s_movk_i32 s0, 0xffa0
	v_mul_f32_e32 v120, v102, v130
	v_pk_mul_f32 v[124:125], v[96:97], v[130:131]
	v_mov_b32_e32 v102, v111
	v_mad_i32_i24 v96, v132, s0, v121
	v_cvt_pk_bf16_f32 v166, v166, v167
	v_cvt_pk_bf16_f32 v167, v170, v171
	v_pk_mul_f32 v[104:105], v[104:105], v[130:131]
	v_pk_mul_f32 v[126:127], v[98:99], v[130:131]
	v_pk_mul_f32 v[106:107], v[106:107], v[130:131]
	v_pk_mul_f32 v[122:123], v[100:101], v[130:131]
	v_pk_mul_f32 v[100:101], v[108:109], v[130:131]
	v_mul_f32_e32 v108, v110, v130
	v_pk_mul_f32 v[102:103], v[102:103], v[130:131]
	v_cmp_eq_u32_e64 s[14:15], 64, v96
	global_store_dwordx2 v[172:173], v[166:167], off
	global_store_dwordx2 v[172:173], v[164:165], off offset:16
	s_and_saveexec_b64 s[2:3], s[14:15]
	s_cbranch_execz .LBB0_1235
	global_load_dwordx4 v[96:99], v[118:119], off
	global_load_dwordx4 v[164:167], v[116:117], off
	global_load_dwordx4 v[236:239], v[118:119], off offset:32
	global_load_dwordx4 v[240:243], v[116:117], off offset:32
	v_mov_b32_e32 v109, v102
	v_mov_b32_e32 v121, v103
	s_waitcnt vmcnt(0)
	v_pk_mul_f32 v[110:111], v[104:105], v[164:165]
	s_nop 0
	v_pk_fma_f32 v[110:111], v[124:125], v[96:97], v[110:111] neg_lo:[0,0,1] neg_hi:[0,0,1]
	v_pk_mul_f32 v[124:125], v[124:125], v[164:165]
	s_nop 0
	v_pk_fma_f32 v[104:105], v[104:105], v[96:97], v[124:125]
	v_pk_mul_f32 v[96:97], v[106:107], v[166:167]
	s_nop 0
	v_pk_fma_f32 v[130:131], v[126:127], v[98:99], v[96:97] neg_lo:[0,0,1] neg_hi:[0,0,1]
	v_pk_mul_f32 v[96:97], v[126:127], v[166:167]
	v_mov_b32_e32 v126, v130
	v_pk_fma_f32 v[106:107], v[106:107], v[98:99], v[96:97]
	s_nop 0
	v_mov_b32_e32 v127, v131
	v_pk_mul_f32 v[124:125], v[100:101], v[240:241]
	v_pk_mul_f32 v[116:117], v[122:123], v[240:241]
	v_pk_fma_f32 v[134:135], v[122:123], v[236:237], v[124:125] neg_lo:[0,0,1] neg_hi:[0,0,1]
	v_pk_fma_f32 v[100:101], v[100:101], v[236:237], v[116:117]
	v_mul_f32_e32 v96, v108, v238
	v_mul_f32_e32 v116, v120, v242
	v_pk_mul_f32 v[108:109], v[108:109], v[242:243]
	v_mov_b32_e32 v118, v239
	v_pk_fma_f32 v[120:121], v[120:121], v[238:239], v[108:109] neg_lo:[0,0,1] neg_hi:[0,0,1]
	v_mov_b32_e32 v119, v243
	v_pk_mul_f32 v[98:99], v[102:103], v[118:119]
	v_mov_b32_e32 v124, v110
	v_mov_b32_e32 v97, v98
	v_mov_b32_e32 v117, v99
	v_pk_add_f32 v[108:109], v[96:97], v[116:117]
	v_mov_b32_e32 v125, v111
	v_mov_b32_e32 v122, v134
	v_mov_b32_e32 v123, v135
	v_mov_b32_e32 v103, v121
	v_mov_b32_e32 v102, v109
.LBB0_1235:
	s_or_b64 exec, exec, s[2:3]
	v_add_u32_e32 v96, v133, v132
	v_ashrrev_i32_e32 v97, 31, v96
	v_lshlrev_b64 v[96:97], 13, v[96:97]
	v_mul_i32_i24_e32 v98, 0xffffffa0, v132
	v_or_b32_e32 v99, v96, v129
	v_mov_b64_e32 v[110:111], s[20:21]
	v_mad_u64_u32 v[110:111], s[0:1], v99, s77, v[110:111]
	v_ashrrev_i32_e32 v99, 31, v98
	v_ashrrev_i32_e32 v163, 31, v162
	v_mad_i32_i24 v111, v97, s77, v111
	v_lshl_add_u64 v[98:99], v[98:99], 0, v[162:163]
	v_lshl_add_u64 v[110:111], v[98:99], 1, v[110:111]
	v_lshl_add_u64 v[110:111], v[110:111], 0, v[168:169]
	v_cvt_pk_bf16_f32 v116, v124, v125
	v_cvt_pk_bf16_f32 v117, v126, v127
	global_store_dwordx2 v[110:111], v[116:117], off offset:64
	v_cvt_pk_bf16_f32 v117, v120, v103
	ds_read_b32 v103, v210 offset:128
	v_cvt_pk_bf16_f32 v104, v104, v105
	v_cvt_pk_bf16_f32 v105, v106, v107
	global_store_dwordx2 v[110:111], v[104:105], off offset:96
	v_or_b32_e32 v104, 32, v128
	v_cvt_pk_bf16_f32 v116, v122, v123
	v_cvt_pk_bf16_f32 v100, v100, v101
	v_cvt_pk_bf16_f32 v101, v108, v102
	v_ashrrev_i32_e32 v105, 31, v104
	global_store_dwordx2 v[110:111], v[116:117], off offset:80
	global_store_dwordx2 v[110:111], v[100:101], off offset:112
	s_waitcnt lgkmcnt(0)
	v_mul_f32_e32 v100, 0x3e16c740, v103
	v_lshlrev_b64 v[116:117], 4, v[104:105]
	v_mul_f32_e32 v102, v86, v100
	v_pk_mul_f32 v[108:109], v[80:81], v[100:101] op_sel_hi:[1,0]
	v_mov_b32_e32 v86, v95
	v_lshlrev_b64 v[80:81], 2, v[116:117]
	v_pk_mul_f32 v[88:89], v[88:89], v[100:101] op_sel_hi:[1,0]
	v_pk_mul_f32 v[110:111], v[82:83], v[100:101] op_sel_hi:[1,0]
	v_pk_mul_f32 v[90:91], v[90:91], v[100:101] op_sel_hi:[1,0]
	v_pk_mul_f32 v[106:107], v[84:85], v[100:101] op_sel_hi:[1,0]
	v_pk_mul_f32 v[84:85], v[92:93], v[100:101] op_sel_hi:[1,0]
	v_mul_f32_e32 v92, v94, v100
	v_pk_mul_f32 v[86:87], v[86:87], v[100:101] op_sel_hi:[1,0]
	v_lshl_add_u64 v[82:83], v[148:149], 0, v[80:81]
	v_lshl_add_u64 v[80:81], v[150:151], 0, v[80:81]
	s_and_saveexec_b64 s[2:3], vcc
	s_cbranch_execz .LBB0_1237
	global_load_dwordx4 v[116:119], v[82:83], off
	global_load_dwordx4 v[120:123], v[80:81], off
	global_load_dwordx4 v[236:239], v[82:83], off offset:32
	global_load_dwordx4 v[240:243], v[80:81], off offset:32
	v_mov_b32_e32 v93, v86
	v_mov_b32_e32 v103, v87
	s_waitcnt vmcnt(0)
	v_pk_mul_f32 v[94:95], v[88:89], v[120:121]
	s_nop 0
	v_pk_fma_f32 v[94:95], v[108:109], v[116:117], v[94:95] neg_lo:[0,0,1] neg_hi:[0,0,1]
	v_pk_mul_f32 v[108:109], v[108:109], v[120:121]
	s_nop 0
	v_pk_fma_f32 v[88:89], v[88:89], v[116:117], v[108:109]
	v_pk_mul_f32 v[108:109], v[90:91], v[122:123]
	s_nop 0
	v_pk_fma_f32 v[120:121], v[110:111], v[118:119], v[108:109] neg_lo:[0,0,1] neg_hi:[0,0,1]
	v_pk_mul_f32 v[108:109], v[110:111], v[122:123]
	s_nop 0
	v_pk_fma_f32 v[90:91], v[90:91], v[118:119], v[108:109]
	v_pk_mul_f32 v[122:123], v[84:85], v[240:241]
	s_nop 0
	v_pk_fma_f32 v[122:123], v[106:107], v[236:237], v[122:123] neg_lo:[0,0,1] neg_hi:[0,0,1]
	v_pk_mul_f32 v[106:107], v[106:107], v[240:241]
	s_nop 0
	v_pk_fma_f32 v[84:85], v[84:85], v[236:237], v[106:107]
	v_mul_f32_e32 v106, v92, v238
	v_mul_f32_e32 v108, v102, v242
	v_pk_mul_f32 v[92:93], v[92:93], v[242:243]
	v_mov_b32_e32 v118, v239
	v_mov_b32_e32 v119, v243
	v_pk_mul_f32 v[86:87], v[86:87], v[118:119]
	v_pk_fma_f32 v[102:103], v[102:103], v[238:239], v[92:93] neg_lo:[0,0,1] neg_hi:[0,0,1]
	v_mov_b32_e32 v107, v86
	v_mov_b32_e32 v109, v87
	v_pk_add_f32 v[92:93], v[106:107], v[108:109]
	v_mov_b32_e32 v108, v94
	v_mov_b32_e32 v109, v95
	v_mov_b32_e32 v110, v120
	v_mov_b32_e32 v111, v121
	v_mov_b32_e32 v106, v122
	v_mov_b32_e32 v107, v123
	v_mov_b32_e32 v87, v103
	v_mov_b32_e32 v86, v93
	v_mov_b32_e32 v116, v240
	v_mov_b32_e32 v117, v241
.LBB0_1237:
	s_or_b64 exec, exec, s[2:3]
	v_and_b32_e32 v93, 0x1fbf, v104
	v_or_b32_e32 v103, v114, v93
	v_mov_b64_e32 v[94:95], s[20:21]
	v_mad_u64_u32 v[94:95], s[0:1], v103, s77, v[94:95]
	v_mad_i32_i24 v95, v115, s77, v95
	v_lshl_add_u64 v[94:95], v[112:113], 1, v[94:95]
	v_lshl_add_u64 v[94:95], v[94:95], 0, v[168:169]
	v_cvt_pk_bf16_f32 v84, v84, v85
	v_cvt_pk_bf16_f32 v85, v92, v86
	v_mov_b32_e32 v101, v100
	v_cvt_pk_bf16_f32 v104, v108, v109
	v_cvt_pk_bf16_f32 v105, v110, v111
	v_cvt_pk_bf16_f32 v88, v88, v89
	v_cvt_pk_bf16_f32 v89, v90, v91
	global_store_dwordx2 v[94:95], v[84:85], off offset:48
	v_mul_f32_e32 v84, v70, v100
	v_mov_b32_e32 v70, v79
	global_store_dwordx2 v[94:95], v[104:105], off
	v_cvt_pk_bf16_f32 v104, v106, v107
	v_cvt_pk_bf16_f32 v105, v102, v87
	global_store_dwordx2 v[94:95], v[88:89], off offset:32
	v_pk_mul_f32 v[88:89], v[64:65], v[100:101]
	v_pk_mul_f32 v[64:65], v[72:73], v[100:101]
	v_pk_mul_f32 v[90:91], v[66:67], v[100:101]
	v_pk_mul_f32 v[72:73], v[74:75], v[100:101]
	v_pk_mul_f32 v[86:87], v[68:69], v[100:101]
	v_pk_mul_f32 v[66:67], v[76:77], v[100:101]
	v_mul_f32_e32 v74, v78, v100
	v_pk_mul_f32 v[68:69], v[70:71], v[100:101]
	global_store_dwordx2 v[94:95], v[104:105], off offset:16
	s_and_saveexec_b64 s[2:3], s[14:15]
	s_cbranch_execz .LBB0_1239
	global_load_dwordx4 v[76:79], v[82:83], off
	global_load_dwordx4 v[100:103], v[80:81], off
	global_load_dwordx4 v[236:239], v[82:83], off offset:32
	global_load_dwordx4 v[240:243], v[80:81], off offset:32
	v_mov_b32_e32 v75, v68
	v_mov_b32_e32 v85, v69
	s_waitcnt vmcnt(0)
	v_pk_mul_f32 v[70:71], v[64:65], v[100:101]
	s_nop 0
	v_pk_fma_f32 v[70:71], v[88:89], v[76:77], v[70:71] neg_lo:[0,0,1] neg_hi:[0,0,1]
	v_pk_mul_f32 v[88:89], v[88:89], v[100:101]
	s_nop 0
	v_pk_fma_f32 v[64:65], v[64:65], v[76:77], v[88:89]
	v_pk_mul_f32 v[76:77], v[72:73], v[102:103]
	s_nop 0
	v_pk_fma_f32 v[94:95], v[90:91], v[78:79], v[76:77] neg_lo:[0,0,1] neg_hi:[0,0,1]
	v_pk_mul_f32 v[76:77], v[90:91], v[102:103]
	v_mov_b32_e32 v90, v94
	v_pk_fma_f32 v[72:73], v[72:73], v[78:79], v[76:77]
	s_nop 0
	v_mov_b32_e32 v91, v95
	v_pk_mul_f32 v[88:89], v[66:67], v[240:241]
	v_pk_mul_f32 v[80:81], v[86:87], v[240:241]
	v_pk_fma_f32 v[100:101], v[86:87], v[236:237], v[88:89] neg_lo:[0,0,1] neg_hi:[0,0,1]
	v_pk_fma_f32 v[66:67], v[66:67], v[236:237], v[80:81]
	v_mul_f32_e32 v76, v74, v238
	v_mul_f32_e32 v80, v84, v242
	v_pk_mul_f32 v[74:75], v[74:75], v[242:243]
	v_mov_b32_e32 v82, v239
	v_mov_b32_e32 v83, v243
	v_pk_mul_f32 v[68:69], v[68:69], v[82:83]
	v_pk_fma_f32 v[84:85], v[84:85], v[238:239], v[74:75] neg_lo:[0,0,1] neg_hi:[0,0,1]
	v_mov_b32_e32 v77, v68
	v_mov_b32_e32 v81, v69
	v_pk_add_f32 v[74:75], v[76:77], v[80:81]
	v_mov_b32_e32 v88, v70
	v_mov_b32_e32 v89, v71
	v_mov_b32_e32 v86, v100
	v_mov_b32_e32 v87, v101
	v_mov_b32_e32 v69, v85
	v_mov_b32_e32 v68, v75
	v_mov_b32_e32 v78, v238
	v_mov_b32_e32 v79, v239
.LBB0_1239:
	s_or_b64 exec, exec, s[2:3]
	v_or_b32_e32 v75, v96, v93
	v_mov_b64_e32 v[70:71], s[20:21]
	v_mad_u64_u32 v[70:71], s[0:1], v75, s77, v[70:71]
	v_mad_i32_i24 v71, v97, s77, v71
	v_lshl_add_u64 v[70:71], v[98:99], 1, v[70:71]
	v_lshl_add_u64 v[70:71], v[70:71], 0, v[168:169]
	v_cvt_pk_bf16_f32 v76, v88, v89
	v_cvt_pk_bf16_f32 v77, v90, v91
	global_store_dwordx2 v[70:71], v[76:77], off offset:64
	v_cvt_pk_bf16_f32 v77, v84, v69
	ds_read_b32 v69, v210 offset:256
	v_cvt_pk_bf16_f32 v64, v64, v65
	v_cvt_pk_bf16_f32 v65, v72, v73
	global_store_dwordx2 v[70:71], v[64:65], off offset:96
	v_cvt_pk_bf16_f32 v64, v66, v67
	v_cvt_pk_bf16_f32 v65, v74, v68
	v_or_b32_e32 v68, 64, v128
	v_cvt_pk_bf16_f32 v76, v86, v87
	global_store_dwordx2 v[70:71], v[64:65], off offset:112
	s_waitcnt lgkmcnt(0)
	v_mul_f32_e32 v64, 0x3e16c740, v69
	v_ashrrev_i32_e32 v69, 31, v68
	global_store_dwordx2 v[70:71], v[76:77], off offset:80
	v_lshlrev_b64 v[76:77], 4, v[68:69]
	v_mul_f32_e32 v66, v54, v64
	v_pk_mul_f32 v[72:73], v[48:49], v[64:65] op_sel_hi:[1,0]
	v_mov_b32_e32 v54, v63
	v_lshlrev_b64 v[48:49], 2, v[76:77]
	v_pk_mul_f32 v[56:57], v[56:57], v[64:65] op_sel_hi:[1,0]
	v_pk_mul_f32 v[74:75], v[50:51], v[64:65] op_sel_hi:[1,0]
	v_pk_mul_f32 v[58:59], v[58:59], v[64:65] op_sel_hi:[1,0]
	v_pk_mul_f32 v[70:71], v[52:53], v[64:65] op_sel_hi:[1,0]
	v_pk_mul_f32 v[52:53], v[60:61], v[64:65] op_sel_hi:[1,0]
	v_mul_f32_e32 v60, v62, v64
	v_pk_mul_f32 v[54:55], v[54:55], v[64:65] op_sel_hi:[1,0]
	v_lshl_add_u64 v[50:51], v[148:149], 0, v[48:49]
	v_lshl_add_u64 v[48:49], v[150:151], 0, v[48:49]
	s_and_saveexec_b64 s[2:3], vcc
	s_cbranch_execz .LBB0_1241
	global_load_dwordx4 v[76:79], v[50:51], off
	global_load_dwordx4 v[80:83], v[48:49], off
	global_load_dwordx4 v[236:239], v[50:51], off offset:32
	global_load_dwordx4 v[240:243], v[48:49], off offset:32
	v_mov_b32_e32 v61, v54
	v_mov_b32_e32 v67, v55
	s_waitcnt vmcnt(0)
	v_pk_mul_f32 v[62:63], v[56:57], v[80:81]
	s_nop 0
	v_pk_fma_f32 v[62:63], v[72:73], v[76:77], v[62:63] neg_lo:[0,0,1] neg_hi:[0,0,1]
	v_pk_mul_f32 v[72:73], v[72:73], v[80:81]
	s_nop 0
	v_pk_fma_f32 v[56:57], v[56:57], v[76:77], v[72:73]
	v_pk_mul_f32 v[72:73], v[58:59], v[82:83]
	s_nop 0
	v_pk_fma_f32 v[80:81], v[74:75], v[78:79], v[72:73] neg_lo:[0,0,1] neg_hi:[0,0,1]
	v_pk_mul_f32 v[72:73], v[74:75], v[82:83]
	s_nop 0
	v_pk_fma_f32 v[58:59], v[58:59], v[78:79], v[72:73]
	v_pk_mul_f32 v[82:83], v[52:53], v[240:241]
	s_nop 0
	v_pk_fma_f32 v[82:83], v[70:71], v[236:237], v[82:83] neg_lo:[0,0,1] neg_hi:[0,0,1]
	v_pk_mul_f32 v[70:71], v[70:71], v[240:241]
	s_nop 0
	v_pk_fma_f32 v[52:53], v[52:53], v[236:237], v[70:71]
	v_mul_f32_e32 v70, v60, v238
	v_mul_f32_e32 v72, v66, v242
	v_pk_mul_f32 v[60:61], v[60:61], v[242:243]
	v_mov_b32_e32 v78, v239
	v_mov_b32_e32 v79, v243
	v_pk_mul_f32 v[54:55], v[54:55], v[78:79]
	v_pk_fma_f32 v[66:67], v[66:67], v[238:239], v[60:61] neg_lo:[0,0,1] neg_hi:[0,0,1]
	v_mov_b32_e32 v71, v54
	v_mov_b32_e32 v73, v55
	v_pk_add_f32 v[60:61], v[70:71], v[72:73]
	v_mov_b32_e32 v72, v62
	v_mov_b32_e32 v73, v63
	v_mov_b32_e32 v74, v80
	v_mov_b32_e32 v75, v81
	v_mov_b32_e32 v70, v82
	v_mov_b32_e32 v71, v83
	v_mov_b32_e32 v55, v67
	v_mov_b32_e32 v54, v61
	v_mov_b32_e32 v76, v240
	v_mov_b32_e32 v77, v241
.LBB0_1241:
	s_or_b64 exec, exec, s[2:3]
	v_and_b32_e32 v61, 0x1fdf, v68
	v_or_b32_e32 v67, v114, v61
	v_mov_b64_e32 v[62:63], s[20:21]
	v_mad_u64_u32 v[62:63], s[0:1], v67, s77, v[62:63]
	v_mad_i32_i24 v63, v115, s77, v63
	v_lshl_add_u64 v[62:63], v[112:113], 1, v[62:63]
	v_lshl_add_u64 v[62:63], v[62:63], 0, v[168:169]
	v_cvt_pk_bf16_f32 v52, v52, v53
	v_cvt_pk_bf16_f32 v53, v60, v54
	v_mov_b32_e32 v65, v64
	v_cvt_pk_bf16_f32 v68, v72, v73
	v_cvt_pk_bf16_f32 v69, v74, v75
	v_cvt_pk_bf16_f32 v56, v56, v57
	v_cvt_pk_bf16_f32 v57, v58, v59
	global_store_dwordx2 v[62:63], v[52:53], off offset:48
	v_mul_f32_e32 v52, v38, v64
	v_mov_b32_e32 v38, v47
	global_store_dwordx2 v[62:63], v[68:69], off
	v_cvt_pk_bf16_f32 v68, v70, v71
	v_cvt_pk_bf16_f32 v69, v66, v55
	global_store_dwordx2 v[62:63], v[56:57], off offset:32
	v_pk_mul_f32 v[56:57], v[32:33], v[64:65]
	v_pk_mul_f32 v[32:33], v[40:41], v[64:65]
	v_pk_mul_f32 v[58:59], v[34:35], v[64:65]
	v_pk_mul_f32 v[40:41], v[42:43], v[64:65]
	v_pk_mul_f32 v[54:55], v[36:37], v[64:65]
	v_pk_mul_f32 v[34:35], v[44:45], v[64:65]
	v_mul_f32_e32 v42, v46, v64
	v_pk_mul_f32 v[36:37], v[38:39], v[64:65]
	global_store_dwordx2 v[62:63], v[68:69], off offset:16
	s_and_saveexec_b64 s[2:3], s[14:15]
	s_cbranch_execz .LBB0_1243
	global_load_dwordx4 v[44:47], v[50:51], off
	global_load_dwordx4 v[62:65], v[48:49], off
	global_load_dwordx4 v[236:239], v[50:51], off offset:32
	global_load_dwordx4 v[240:243], v[48:49], off offset:32
	v_mov_b32_e32 v43, v36
	v_mov_b32_e32 v53, v37
	s_waitcnt vmcnt(0)
	v_pk_mul_f32 v[38:39], v[32:33], v[62:63]
	s_nop 0
	v_pk_fma_f32 v[38:39], v[56:57], v[44:45], v[38:39] neg_lo:[0,0,1] neg_hi:[0,0,1]
	v_pk_mul_f32 v[56:57], v[56:57], v[62:63]
	s_nop 0
	v_pk_fma_f32 v[32:33], v[32:33], v[44:45], v[56:57]
	v_pk_mul_f32 v[44:45], v[40:41], v[64:65]
	s_nop 0
	v_pk_fma_f32 v[62:63], v[58:59], v[46:47], v[44:45] neg_lo:[0,0,1] neg_hi:[0,0,1]
	v_pk_mul_f32 v[44:45], v[58:59], v[64:65]
	v_mov_b32_e32 v58, v62
	v_pk_fma_f32 v[40:41], v[40:41], v[46:47], v[44:45]
	s_nop 0
	v_mov_b32_e32 v59, v63
	v_pk_mul_f32 v[56:57], v[34:35], v[240:241]
	v_pk_mul_f32 v[48:49], v[54:55], v[240:241]
	v_pk_fma_f32 v[64:65], v[54:55], v[236:237], v[56:57] neg_lo:[0,0,1] neg_hi:[0,0,1]
	v_pk_fma_f32 v[34:35], v[34:35], v[236:237], v[48:49]
	v_mul_f32_e32 v44, v42, v238
	v_mul_f32_e32 v48, v52, v242
	v_pk_mul_f32 v[42:43], v[42:43], v[242:243]
	v_mov_b32_e32 v50, v239
	v_mov_b32_e32 v51, v243
	v_pk_mul_f32 v[36:37], v[36:37], v[50:51]
	v_pk_fma_f32 v[52:53], v[52:53], v[238:239], v[42:43] neg_lo:[0,0,1] neg_hi:[0,0,1]
	v_mov_b32_e32 v45, v36
	v_mov_b32_e32 v49, v37
	v_pk_add_f32 v[42:43], v[44:45], v[48:49]
	v_mov_b32_e32 v56, v38
	v_mov_b32_e32 v57, v39
	v_mov_b32_e32 v54, v64
	v_mov_b32_e32 v55, v65
	v_mov_b32_e32 v37, v53
	v_mov_b32_e32 v36, v43
	v_mov_b32_e32 v46, v238
	v_mov_b32_e32 v47, v239
.LBB0_1243:
	s_or_b64 exec, exec, s[2:3]
	v_or_b32_e32 v43, v96, v61
	v_mov_b64_e32 v[38:39], s[20:21]
	v_mad_u64_u32 v[38:39], s[0:1], v43, s77, v[38:39]
	v_mad_i32_i24 v39, v97, s77, v39
	v_lshl_add_u64 v[38:39], v[98:99], 1, v[38:39]
	v_lshl_add_u64 v[38:39], v[38:39], 0, v[168:169]
	v_cvt_pk_bf16_f32 v44, v56, v57
	v_cvt_pk_bf16_f32 v45, v58, v59
	global_store_dwordx2 v[38:39], v[44:45], off offset:64
	v_cvt_pk_bf16_f32 v45, v52, v37
	ds_read_b32 v37, v210 offset:384
	v_cvt_pk_bf16_f32 v32, v32, v33
	v_cvt_pk_bf16_f32 v33, v40, v41
	global_store_dwordx2 v[38:39], v[32:33], off offset:96
	v_cvt_pk_bf16_f32 v32, v34, v35
	v_cvt_pk_bf16_f32 v33, v42, v36
	v_or_b32_e32 v36, 0x60, v128
	v_cvt_pk_bf16_f32 v44, v54, v55
	global_store_dwordx2 v[38:39], v[32:33], off offset:112
	s_waitcnt lgkmcnt(0)
	v_mul_f32_e32 v32, 0x3e16c740, v37
	v_ashrrev_i32_e32 v37, 31, v36
	global_store_dwordx2 v[38:39], v[44:45], off offset:80
	v_lshlrev_b64 v[44:45], 4, v[36:37]
	v_mul_f32_e32 v34, v22, v32
	v_pk_mul_f32 v[40:41], v[16:17], v[32:33] op_sel_hi:[1,0]
	v_mov_b32_e32 v22, v31
	v_lshlrev_b64 v[16:17], 2, v[44:45]
	v_pk_mul_f32 v[24:25], v[24:25], v[32:33] op_sel_hi:[1,0]
	v_pk_mul_f32 v[42:43], v[18:19], v[32:33] op_sel_hi:[1,0]
	v_pk_mul_f32 v[26:27], v[26:27], v[32:33] op_sel_hi:[1,0]
	v_pk_mul_f32 v[38:39], v[20:21], v[32:33] op_sel_hi:[1,0]
	v_pk_mul_f32 v[20:21], v[28:29], v[32:33] op_sel_hi:[1,0]
	v_mul_f32_e32 v28, v30, v32
	v_pk_mul_f32 v[22:23], v[22:23], v[32:33] op_sel_hi:[1,0]
	v_lshl_add_u64 v[18:19], v[148:149], 0, v[16:17]
	v_lshl_add_u64 v[16:17], v[150:151], 0, v[16:17]
	s_and_saveexec_b64 s[2:3], vcc
	s_cbranch_execz .LBB0_1245
	global_load_dwordx4 v[44:47], v[18:19], off
	global_load_dwordx4 v[48:51], v[16:17], off
	global_load_dwordx4 v[236:239], v[18:19], off offset:32
	global_load_dwordx4 v[240:243], v[16:17], off offset:32
	v_mov_b32_e32 v29, v22
	v_mov_b32_e32 v35, v23
	s_waitcnt vmcnt(0)
	v_pk_mul_f32 v[30:31], v[24:25], v[48:49]
	s_nop 0
	v_pk_fma_f32 v[30:31], v[40:41], v[44:45], v[30:31] neg_lo:[0,0,1] neg_hi:[0,0,1]
	v_pk_mul_f32 v[40:41], v[40:41], v[48:49]
	s_nop 0
	v_pk_fma_f32 v[24:25], v[24:25], v[44:45], v[40:41]
	v_pk_mul_f32 v[40:41], v[26:27], v[50:51]
	s_nop 0
	v_pk_fma_f32 v[48:49], v[42:43], v[46:47], v[40:41] neg_lo:[0,0,1] neg_hi:[0,0,1]
	v_pk_mul_f32 v[40:41], v[42:43], v[50:51]
	s_nop 0
	v_pk_fma_f32 v[26:27], v[26:27], v[46:47], v[40:41]
	v_pk_mul_f32 v[50:51], v[20:21], v[240:241]
	s_nop 0
	v_pk_fma_f32 v[50:51], v[38:39], v[236:237], v[50:51] neg_lo:[0,0,1] neg_hi:[0,0,1]
	v_pk_mul_f32 v[38:39], v[38:39], v[240:241]
	s_nop 0
	v_pk_fma_f32 v[20:21], v[20:21], v[236:237], v[38:39]
	v_mul_f32_e32 v38, v28, v238
	v_mul_f32_e32 v40, v34, v242
	v_pk_mul_f32 v[28:29], v[28:29], v[242:243]
	v_mov_b32_e32 v46, v239
	v_mov_b32_e32 v47, v243
	v_pk_mul_f32 v[22:23], v[22:23], v[46:47]
	v_pk_fma_f32 v[34:35], v[34:35], v[238:239], v[28:29] neg_lo:[0,0,1] neg_hi:[0,0,1]
	v_mov_b32_e32 v39, v22
	v_mov_b32_e32 v41, v23
	v_pk_add_f32 v[28:29], v[38:39], v[40:41]
	v_mov_b32_e32 v40, v30
	v_mov_b32_e32 v41, v31
	v_mov_b32_e32 v42, v48
	v_mov_b32_e32 v43, v49
	v_mov_b32_e32 v38, v50
	v_mov_b32_e32 v39, v51
	v_mov_b32_e32 v23, v35
	v_mov_b32_e32 v22, v29
	v_mov_b32_e32 v44, v240
	v_mov_b32_e32 v45, v241
.LBB0_1245:
	s_or_b64 exec, exec, s[2:3]
	v_and_b32_e32 v29, 0x1fff, v36
	v_or_b32_e32 v35, v114, v29
	v_mov_b64_e32 v[30:31], s[20:21]
	v_mad_u64_u32 v[30:31], s[0:1], v35, s77, v[30:31]
	v_mad_i32_i24 v31, v115, s77, v31
	v_lshl_add_u64 v[30:31], v[112:113], 1, v[30:31]
	v_lshl_add_u64 v[30:31], v[30:31], 0, v[168:169]
	v_cvt_pk_bf16_f32 v20, v20, v21
	v_cvt_pk_bf16_f32 v21, v28, v22
	v_mov_b32_e32 v33, v32
	v_cvt_pk_bf16_f32 v36, v40, v41
	v_cvt_pk_bf16_f32 v37, v42, v43
	v_cvt_pk_bf16_f32 v24, v24, v25
	v_cvt_pk_bf16_f32 v25, v26, v27
	global_store_dwordx2 v[30:31], v[20:21], off offset:48
	v_mul_f32_e32 v20, v6, v32
	v_mov_b32_e32 v6, v15
	global_store_dwordx2 v[30:31], v[36:37], off
	v_cvt_pk_bf16_f32 v36, v38, v39
	v_cvt_pk_bf16_f32 v37, v34, v23
	global_store_dwordx2 v[30:31], v[24:25], off offset:32
	v_pk_mul_f32 v[22:23], v[0:1], v[32:33]
	v_pk_mul_f32 v[0:1], v[8:9], v[32:33]
	v_pk_mul_f32 v[24:25], v[2:3], v[32:33]
	v_pk_mul_f32 v[2:3], v[10:11], v[32:33]
	v_pk_mul_f32 v[10:11], v[4:5], v[32:33]
	v_pk_mul_f32 v[4:5], v[12:13], v[32:33]
	v_mul_f32_e32 v8, v14, v32
	v_pk_mul_f32 v[6:7], v[6:7], v[32:33]
	global_store_dwordx2 v[30:31], v[36:37], off offset:16
	s_and_saveexec_b64 s[2:3], s[14:15]
	s_cbranch_execz .LBB0_1247
	global_load_dwordx4 v[12:15], v[18:19], off
	global_load_dwordx4 v[30:33], v[16:17], off
	global_load_dwordx4 v[236:239], v[18:19], off offset:32
	global_load_dwordx4 v[240:243], v[16:17], off offset:32
	v_mov_b32_e32 v9, v6
	v_mov_b32_e32 v21, v7
	s_waitcnt vmcnt(0)
	v_pk_mul_f32 v[26:27], v[0:1], v[30:31]
	s_nop 0
	v_pk_fma_f32 v[26:27], v[22:23], v[12:13], v[26:27] neg_lo:[0,0,1] neg_hi:[0,0,1]
	v_pk_mul_f32 v[22:23], v[22:23], v[30:31]
	s_nop 0
	v_pk_fma_f32 v[0:1], v[0:1], v[12:13], v[22:23]
	v_pk_mul_f32 v[12:13], v[2:3], v[32:33]
	s_nop 0
	v_pk_fma_f32 v[30:31], v[24:25], v[14:15], v[12:13] neg_lo:[0,0,1] neg_hi:[0,0,1]
	v_pk_mul_f32 v[12:13], v[24:25], v[32:33]
	v_mov_b32_e32 v24, v30
	v_pk_fma_f32 v[2:3], v[2:3], v[14:15], v[12:13]
	s_nop 0
	v_mov_b32_e32 v25, v31
	v_pk_mul_f32 v[22:23], v[4:5], v[240:241]
	s_nop 0
	v_pk_fma_f32 v[32:33], v[10:11], v[236:237], v[22:23] neg_lo:[0,0,1] neg_hi:[0,0,1]
	v_pk_mul_f32 v[10:11], v[10:11], v[240:241]
	v_mov_b32_e32 v22, v26
	v_pk_fma_f32 v[4:5], v[4:5], v[236:237], v[10:11]
	v_mul_f32_e32 v10, v8, v238
	v_mul_f32_e32 v12, v20, v242
	v_pk_mul_f32 v[8:9], v[8:9], v[242:243]
	v_mov_b32_e32 v18, v239
	v_mov_b32_e32 v19, v243
	v_pk_mul_f32 v[6:7], v[6:7], v[18:19]
	v_pk_fma_f32 v[20:21], v[20:21], v[238:239], v[8:9] neg_lo:[0,0,1] neg_hi:[0,0,1]
	v_mov_b32_e32 v11, v6
	v_mov_b32_e32 v13, v7
	v_pk_add_f32 v[8:9], v[10:11], v[12:13]
	v_mov_b32_e32 v23, v27
	v_mov_b32_e32 v10, v32
	v_mov_b32_e32 v11, v33
	v_mov_b32_e32 v7, v21
	v_mov_b32_e32 v6, v9
	v_mov_b32_e32 v14, v238
	v_mov_b32_e32 v15, v239
	v_mov_b32_e32 v16, v240
	v_mov_b32_e32 v17, v241
